# attention steady loops: 4 no-op v_add_f32 (x+0) removed from the row-sum chains
# baseline (speedup 1.0000x reference)
.LBB0_396:
	s_mov_b32 s36, s66
	s_mov_b32 s5, s40
	s_mov_b32 s6, s3
	v_lshl_add_u32 v195, s37, 1, v230
	ds_read_b64_tr_b16 v[196:197], v195 offset:24576
	ds_read_b64_tr_b16 v[198:199], v195 offset:25088
	v_add_f32_e32 v96, v64, v65
	v_add_f32_e32 v96, v66, v96
	v_add_f32_e32 v96, v67, v96
	v_add_f32_e32 v96, v68, v96
	v_add_f32_e32 v96, v69, v96
	v_cvt_pk_bf16_f32 v144, v64, v65
	v_cvt_pk_bf16_f32 v145, v66, v67
	s_waitcnt lgkmcnt(9)
	v_mfma_f32_32x32x16_bf16 v[112:127], v[188:191], v[128:131], 0
	ds_read_b64_tr_b16 v[64:65], v195 offset:28672
	ds_read_b64_tr_b16 v[66:67], v195 offset:29184
	v_add_f32_e32 v96, v70, v96
	v_add_f32_e32 v96, v71, v96
	v_add_f32_e32 v96, v72, v96
	v_add_f32_e32 v148, v73, v96
	v_cvt_pk_bf16_f32 v146, v68, v69
	v_cvt_pk_bf16_f32 v147, v70, v71
	s_waitcnt lgkmcnt(10)
	v_mfma_f32_32x32x16_bf16 v[96:111], v[180:183], v[128:131], 0
	ds_read_b64_tr_b16 v[68:69], v195 offset:25600
	ds_read_b64_tr_b16 v[70:71], v195 offset:26112
	v_add_f32_e32 v148, v74, v148
	v_add_f32_e32 v148, v75, v148
	v_add_f32_e32 v148, v76, v148
	v_add_f32_e32 v152, v77, v148
	v_cvt_pk_bf16_f32 v148, v72, v73
	v_cvt_pk_bf16_f32 v149, v74, v75
	s_waitcnt lgkmcnt(11)
	v_mfma_f32_32x32x16_bf16 v[112:127], v[184:187], v[132:135], v[112:127]
	ds_read_b64_tr_b16 v[72:73], v195 offset:29696
	ds_read_b64_tr_b16 v[74:75], v195 offset:30208
	v_add_f32_e32 v150, v78, v152
	v_add_f32_e32 v150, v79, v150
	v_add_f32_e32 v150, v80, v150
	v_add_f32_e32 v152, v81, v150
	v_cvt_pk_bf16_f32 v150, v76, v77
	v_cvt_pk_bf16_f32 v151, v78, v79
	s_waitcnt lgkmcnt(12)
	v_mfma_f32_32x32x16_bf16 v[96:111], v[176:179], v[132:135], v[96:111]
	ds_read_b64_tr_b16 v[76:77], v195 offset:26624
	ds_read_b64_tr_b16 v[78:79], v195 offset:27136
	v_add_f32_e32 v152, v82, v152
	v_add_f32_e32 v152, v83, v152
	v_add_f32_e32 v152, v84, v152
	v_add_f32_e32 v156, v85, v152
	v_cvt_pk_bf16_f32 v152, v80, v81
	v_cvt_pk_bf16_f32 v153, v82, v83
	s_waitcnt lgkmcnt(13)
	v_mfma_f32_32x32x16_bf16 v[112:127], v[172:175], v[136:139], v[112:127]
	ds_read_b64_tr_b16 v[200:201], v195 offset:30720
	ds_read_b64_tr_b16 v[202:203], v195 offset:31232
	v_add_f32_e32 v80, v86, v156
	v_add_f32_e32 v80, v87, v80
	v_add_f32_e32 v80, v88, v80
	v_add_f32_e32 v80, v89, v80
	v_cvt_pk_bf16_f32 v154, v84, v85
	v_cvt_pk_bf16_f32 v155, v86, v87
	s_waitcnt lgkmcnt(14)
	v_mfma_f32_32x32x16_bf16 v[96:111], v[168:171], v[136:139], v[96:111]
	ds_read_b64_tr_b16 v[84:85], v195 offset:27648
	ds_read_b64_tr_b16 v[86:87], v195 offset:28160
	v_add_f32_e32 v80, v90, v80
	v_add_f32_e32 v80, v91, v80
	v_add_f32_e32 v80, v92, v80
	v_add_f32_e32 v80, v93, v80
	v_cvt_pk_bf16_f32 v156, v88, v89
	v_cvt_pk_bf16_f32 v157, v90, v91
	s_waitcnt lgkmcnt(14)
	v_mfma_f32_32x32x16_bf16 v[112:127], v[164:167], v[140:143], v[112:127]
	ds_read_b64_tr_b16 v[88:89], v195 offset:31744
	ds_read_b64_tr_b16 v[90:91], v195 offset:32256
	v_add_f32_e32 v80, v94, v80
	v_add_f32_e32 v80, v95, v80
	v_cvt_pk_bf16_f32 v158, v92, v93
	v_cvt_pk_bf16_f32 v159, v94, v95
	v_mfma_f32_32x32x16_bf16 v[96:111], v[160:163], v[140:143], v[96:111]
	s_add_i32 s3, s3, s2
	v_add_f32_e32 v188, v231, v80
	s_mov_b32 m0, s3
	s_add_u32 s100, s98, s72
	s_addc_u32 s101, s99, s73
	global_load_lds_dwordx4 v238, s[100:101]
	s_lshl_b32 s3, s66, 1
	s_add_i32 s3, s3, s35
	s_mov_b32 m0, s3
	s_add_u32 s100, s98, s74
	s_addc_u32 s101, s99, s75
	global_load_lds_dwordx4 v239, s[100:101]
	s_addk_i32 s3, 0x2000
	s_mov_b32 m0, s3
	s_add_u32 s100, s98, s76
	s_addc_u32 s101, s99, s77
	global_load_lds_dwordx4 v239, s[100:101]
	s_waitcnt lgkmcnt(14)
	v_mfma_f32_32x32x16_bf16 v[0:15], v[144:147], v[196:199], v[0:15]
	v_exp_f32_e32 v112, v112
	v_exp_f32_e32 v113, v113
	ds_read_b64_tr_b16 v[92:93], v195 offset:32768
	ds_read_b64_tr_b16 v[94:95], v195 offset:33280
	s_waitcnt lgkmcnt(14)
	v_mfma_f32_32x32x16_bf16 v[16:31], v[144:147], v[64:67], v[16:31]
	v_exp_f32_e32 v114, v114
	v_exp_f32_e32 v115, v115
	ds_read_b64_tr_b16 v[196:197], v195 offset:36864
	ds_read_b64_tr_b16 v[198:199], v195 offset:37376
	v_add_u32_e32 v160, s36, v229
	ds_read_b128 v[64:67], v160
	ds_read_b128 v[80:83], v160 offset:512
	s_waitcnt lgkmcnt(14)
	v_mfma_f32_32x32x16_bf16 v[0:15], v[148:151], v[68:71], v[0:15]
	v_exp_f32_e32 v116, v116
	v_exp_f32_e32 v117, v117
	ds_read_b64_tr_b16 v[68:69], v195 offset:33792
	ds_read_b64_tr_b16 v[70:71], v195 offset:34304
	ds_read_b128 v[180:183], v160 offset:2048
	ds_read_b128 v[176:179], v160 offset:2560
	v_mfma_f32_32x32x16_bf16 v[16:31], v[148:151], v[72:75], v[16:31]
	v_exp_f32_e32 v118, v118
	v_exp_f32_e32 v119, v119
	ds_read_b64_tr_b16 v[72:73], v195 offset:37888
	ds_read_b64_tr_b16 v[74:75], v195 offset:38400
	ds_read_b128 v[172:175], v160 offset:4096
	ds_read_b128 v[168:171], v160 offset:4608
	s_waitcnt lgkmcnt(14)
	v_mfma_f32_32x32x16_bf16 v[0:15], v[152:155], v[76:79], v[0:15]
	v_exp_f32_e32 v120, v120
	v_exp_f32_e32 v121, v121
	ds_read_b64_tr_b16 v[76:77], v195 offset:34816
	ds_read_b64_tr_b16 v[78:79], v195 offset:35328
	ds_read_b128 v[164:167], v160 offset:6144
	ds_read_b128 v[160:163], v160 offset:6656
	v_mfma_f32_32x32x16_bf16 v[16:31], v[152:155], v[200:203], v[16:31]
	v_exp_f32_e32 v122, v122
	v_exp_f32_e32 v123, v123
	ds_read_b64_tr_b16 v[200:201], v195 offset:38912
	ds_read_b64_tr_b16 v[202:203], v195 offset:39424
	v_mfma_f32_32x32x16_bf16 v[0:15], v[156:159], v[84:87], v[0:15]
	v_exp_f32_e32 v124, v124
	v_exp_f32_e32 v125, v125
	ds_read_b64_tr_b16 v[84:85], v195 offset:35840
	ds_read_b64_tr_b16 v[86:87], v195 offset:36352
	v_mfma_f32_32x32x16_bf16 v[16:31], v[156:159], v[88:91], v[16:31]
	v_exp_f32_e32 v126, v126
	v_exp_f32_e32 v127, v127
	ds_read_b64_tr_b16 v[88:89], v195 offset:39936
	ds_read_b64_tr_b16 v[90:91], v195 offset:40448
	s_waitcnt lgkmcnt(14)
	v_mfma_f32_32x32x16_bf16 v[32:47], v[144:147], v[92:95], v[32:47]
	v_exp_f32_e32 v96, v96
	v_exp_f32_e32 v97, v97
	v_mfma_f32_32x32x16_bf16 v[48:63], v[144:147], v[196:199], v[48:63]
	v_exp_f32_e32 v98, v98
	v_exp_f32_e32 v99, v99
	v_mfma_f32_32x32x16_bf16 v[32:47], v[148:151], v[68:71], v[32:47]
	v_exp_f32_e32 v100, v100
	v_exp_f32_e32 v101, v101
	s_waitcnt lgkmcnt(12)
	v_mfma_f32_32x32x16_bf16 v[48:63], v[148:151], v[72:75], v[48:63]
	v_exp_f32_e32 v102, v102
	v_exp_f32_e32 v103, v103
	s_waitcnt lgkmcnt(8)
	v_mfma_f32_32x32x16_bf16 v[32:47], v[152:155], v[76:79], v[32:47]
	v_exp_f32_e32 v104, v104
	v_exp_f32_e32 v105, v105
	s_waitcnt lgkmcnt(4)
	v_mfma_f32_32x32x16_bf16 v[48:63], v[152:155], v[200:203], v[48:63]
	v_exp_f32_e32 v106, v106
	v_exp_f32_e32 v107, v107
	s_waitcnt lgkmcnt(2)
	v_mfma_f32_32x32x16_bf16 v[32:47], v[156:159], v[84:87], v[32:47]
	v_exp_f32_e32 v108, v108
	v_exp_f32_e32 v109, v109
	s_waitcnt lgkmcnt(0)
	v_mfma_f32_32x32x16_bf16 v[48:63], v[156:159], v[88:91], v[48:63]
	v_exp_f32_e32 v110, v110
	v_exp_f32_e32 v111, v111
	s_waitcnt vmcnt(3) lgkmcnt(0)
	s_barrier
	s_add_i32 s3, s66, 0x2000
	s_cmpk_lg_i32 s66, 0x4000
	s_cselect_b32 s3, s3, 0
	v_lshl_add_u32 v195, s6, 1, v230
	ds_read_b64_tr_b16 v[196:197], v195 offset:24576
	ds_read_b64_tr_b16 v[198:199], v195 offset:25088
	v_add_f32_e32 v68, v112, v113
	v_add_f32_e32 v68, v114, v68
	v_add_f32_e32 v68, v115, v68
	v_add_f32_e32 v68, v116, v68
	v_add_f32_e32 v84, v117, v68
	v_mfma_f32_32x32x16_bf16 v[64:79], v[64:67], v[128:131], 0
	v_cvt_pk_bf16_f32 v144, v112, v113
	v_cvt_pk_bf16_f32 v145, v114, v115
	ds_read_b64_tr_b16 v[112:113], v195 offset:28672
	ds_read_b64_tr_b16 v[114:115], v195 offset:29184
	v_add_f32_e32 v84, v118, v84
	v_add_f32_e32 v84, v119, v84
	v_add_f32_e32 v84, v120, v84
	v_add_f32_e32 v148, v121, v84
	v_mfma_f32_32x32x16_bf16 v[80:95], v[80:83], v[128:131], 0
	v_cvt_pk_bf16_f32 v146, v116, v117
	v_cvt_pk_bf16_f32 v147, v118, v119
	ds_read_b64_tr_b16 v[116:117], v195 offset:25600
	ds_read_b64_tr_b16 v[118:119], v195 offset:26112
	v_mfma_f32_32x32x16_bf16 v[64:79], v[180:183], v[132:135], v[64:79]
	v_add_f32_e32 v148, v122, v148
	v_add_f32_e32 v148, v123, v148
	v_add_f32_e32 v148, v124, v148
	v_add_f32_e32 v152, v125, v148
	v_cvt_pk_bf16_f32 v148, v120, v121
	v_cvt_pk_bf16_f32 v149, v122, v123
	ds_read_b64_tr_b16 v[120:121], v195 offset:29696
	ds_read_b64_tr_b16 v[122:123], v195 offset:30208
	v_mfma_f32_32x32x16_bf16 v[80:95], v[176:179], v[132:135], v[80:95]
	v_add_f32_e32 v150, v126, v152
	v_add_f32_e32 v150, v127, v150
	v_add_f32_e32 v150, v96, v150
	v_add_f32_e32 v152, v97, v150
	v_cvt_pk_bf16_f32 v150, v124, v125
	v_cvt_pk_bf16_f32 v151, v126, v127
	ds_read_b64_tr_b16 v[124:125], v195 offset:26624
	ds_read_b64_tr_b16 v[126:127], v195 offset:27136
	v_mfma_f32_32x32x16_bf16 v[64:79], v[172:175], v[136:139], v[64:79]
	v_add_f32_e32 v152, v98, v152
	v_add_f32_e32 v152, v99, v152
	v_add_f32_e32 v152, v100, v152
	v_add_f32_e32 v156, v101, v152
	v_cvt_pk_bf16_f32 v152, v96, v97
	v_cvt_pk_bf16_f32 v153, v98, v99
	ds_read_b64_tr_b16 v[96:97], v195 offset:30720
	ds_read_b64_tr_b16 v[98:99], v195 offset:31232
	v_mfma_f32_32x32x16_bf16 v[80:95], v[168:171], v[136:139], v[80:95]
	v_add_f32_e32 v154, v102, v156
	v_add_f32_e32 v154, v103, v154
	v_add_f32_e32 v154, v104, v154
	v_add_f32_e32 v156, v105, v154
	v_cvt_pk_bf16_f32 v154, v100, v101
	v_cvt_pk_bf16_f32 v155, v102, v103
	ds_read_b64_tr_b16 v[100:101], v195 offset:27648
	ds_read_b64_tr_b16 v[102:103], v195 offset:28160
	v_mfma_f32_32x32x16_bf16 v[64:79], v[164:167], v[140:143], v[64:79]
	v_add_f32_e32 v156, v106, v156
	v_add_f32_e32 v156, v107, v156
	v_add_f32_e32 v156, v108, v156
	v_add_f32_e32 v164, v109, v156
	v_cvt_pk_bf16_f32 v156, v104, v105
	v_cvt_pk_bf16_f32 v157, v106, v107
	ds_read_b64_tr_b16 v[104:105], v195 offset:31744
	ds_read_b64_tr_b16 v[106:107], v195 offset:32256
	v_mfma_f32_32x32x16_bf16 v[80:95], v[160:163], v[140:143], v[80:95]
	v_add_f32_e32 v158, v110, v164
	v_add_f32_e32 v160, v111, v158
	v_cvt_pk_bf16_f32 v158, v108, v109
	v_cvt_pk_bf16_f32 v159, v110, v111
	s_add_i32 s6, s66, s2
	s_mov_b32 m0, s6
	s_add_u32 s100, s98, s78
	s_addc_u32 s101, s99, s79
	global_load_lds_dwordx4 v238, s[100:101]
	s_lshl_b32 s6, s3, 1
	s_add_i32 s6, s6, s35
	s_mov_b32 m0, s6
	s_add_u32 s100, s98, s80
	s_addc_u32 s101, s99, s81
	global_load_lds_dwordx4 v239, s[100:101]
	s_addk_i32 s6, 0x2000
	s_mov_b32 m0, s6
	s_add_u32 s100, s98, s82
	s_addc_u32 s101, s99, s83
	global_load_lds_dwordx4 v239, s[100:101]
	v_add_f32_e32 v231, v188, v160
	s_waitcnt lgkmcnt(14)
	v_mfma_f32_32x32x16_bf16 v[0:15], v[144:147], v[196:199], v[0:15]
	v_exp_f32_e32 v64, v64
	v_exp_f32_e32 v65, v65
	ds_read_b64_tr_b16 v[108:109], v195 offset:32768
	ds_read_b64_tr_b16 v[110:111], v195 offset:33280
	s_waitcnt lgkmcnt(14)
	v_mfma_f32_32x32x16_bf16 v[16:31], v[144:147], v[112:115], v[16:31]
	v_exp_f32_e32 v66, v66
	v_exp_f32_e32 v67, v67
	ds_read_b64_tr_b16 v[112:113], v195 offset:36864
	ds_read_b64_tr_b16 v[114:115], v195 offset:37376
	v_add_u32_e32 v160, s3, v229
	ds_read_b128 v[188:191], v160
	ds_read_b128 v[180:183], v160 offset:512
	s_waitcnt lgkmcnt(14)
	v_mfma_f32_32x32x16_bf16 v[0:15], v[148:151], v[116:119], v[0:15]
	v_exp_f32_e32 v68, v68
	v_exp_f32_e32 v69, v69
	ds_read_b64_tr_b16 v[116:117], v195 offset:33792
	ds_read_b64_tr_b16 v[118:119], v195 offset:34304
	ds_read_b128 v[184:187], v160 offset:2048
	ds_read_b128 v[176:179], v160 offset:2560
	v_mfma_f32_32x32x16_bf16 v[16:31], v[148:151], v[120:123], v[16:31]
	v_exp_f32_e32 v70, v70
	v_exp_f32_e32 v71, v71
	ds_read_b64_tr_b16 v[120:121], v195 offset:37888
	ds_read_b64_tr_b16 v[122:123], v195 offset:38400
	ds_read_b128 v[172:175], v160 offset:4096
	ds_read_b128 v[168:171], v160 offset:4608
	s_waitcnt lgkmcnt(14)
	v_mfma_f32_32x32x16_bf16 v[0:15], v[152:155], v[124:127], v[0:15]
	v_exp_f32_e32 v72, v72
	v_exp_f32_e32 v73, v73
	ds_read_b64_tr_b16 v[124:125], v195 offset:34816
	ds_read_b64_tr_b16 v[126:127], v195 offset:35328
	ds_read_b128 v[164:167], v160 offset:6144
	ds_read_b128 v[160:163], v160 offset:6656
	v_mfma_f32_32x32x16_bf16 v[16:31], v[152:155], v[96:99], v[16:31]
	v_exp_f32_e32 v74, v74
	v_exp_f32_e32 v75, v75
	ds_read_b64_tr_b16 v[96:97], v195 offset:38912
	ds_read_b64_tr_b16 v[98:99], v195 offset:39424
	v_mfma_f32_32x32x16_bf16 v[0:15], v[156:159], v[100:103], v[0:15]
	v_exp_f32_e32 v76, v76
	v_exp_f32_e32 v77, v77
	ds_read_b64_tr_b16 v[100:101], v195 offset:35840
	ds_read_b64_tr_b16 v[102:103], v195 offset:36352
	v_mfma_f32_32x32x16_bf16 v[16:31], v[156:159], v[104:107], v[16:31]
	v_exp_f32_e32 v78, v78
	v_exp_f32_e32 v79, v79
	ds_read_b64_tr_b16 v[104:105], v195 offset:39936
	ds_read_b64_tr_b16 v[106:107], v195 offset:40448
	s_waitcnt lgkmcnt(14)
	v_mfma_f32_32x32x16_bf16 v[32:47], v[144:147], v[108:111], v[32:47]
	v_exp_f32_e32 v80, v80
	v_exp_f32_e32 v81, v81
	v_mfma_f32_32x32x16_bf16 v[48:63], v[144:147], v[112:115], v[48:63]
	v_exp_f32_e32 v82, v82
	v_exp_f32_e32 v83, v83
	v_mfma_f32_32x32x16_bf16 v[32:47], v[148:151], v[116:119], v[32:47]
	v_exp_f32_e32 v84, v84
	v_exp_f32_e32 v85, v85
	s_waitcnt lgkmcnt(12)
	v_mfma_f32_32x32x16_bf16 v[48:63], v[148:151], v[120:123], v[48:63]
	v_exp_f32_e32 v86, v86
	v_exp_f32_e32 v87, v87
	s_waitcnt lgkmcnt(8)
	v_mfma_f32_32x32x16_bf16 v[32:47], v[152:155], v[124:127], v[32:47]
	v_exp_f32_e32 v88, v88
	v_exp_f32_e32 v89, v89
	s_waitcnt lgkmcnt(4)
	v_mfma_f32_32x32x16_bf16 v[48:63], v[152:155], v[96:99], v[48:63]
	v_exp_f32_e32 v90, v90
	v_exp_f32_e32 v91, v91
	s_waitcnt lgkmcnt(2)
	v_mfma_f32_32x32x16_bf16 v[32:47], v[156:159], v[100:103], v[32:47]
	v_exp_f32_e32 v92, v92
	v_exp_f32_e32 v93, v93
	s_waitcnt lgkmcnt(0)
	v_mfma_f32_32x32x16_bf16 v[48:63], v[156:159], v[104:107], v[48:63]
	v_exp_f32_e32 v94, v94
	v_exp_f32_e32 v95, v95
	s_add_i32 s6, s3, 0x2000
	s_cmpk_lg_i32 s3, 0x4000
	s_cselect_b32 s66, s6, 0
	s_add_i32 s40, s40, 2
	s_waitcnt vmcnt(3) lgkmcnt(0)
	s_barrier
	s_add_u32 s38, s38, 0x20000
	s_addc_u32 s39, s39, 0
	s_add_u32 s98, s98, 0x20000
	s_addc_u32 s99, s99, 0
	s_cmp_gt_u32 s40, s57
	s_mov_b32 s37, s36
	s_cbranch_scc0 .LBB0_396
	s_add_i32 s6, s5, -3
	s_xor_b64 s[94:95], s[0:1], -1
	s_cmp_lt_u32 s6, s57
	s_mov_b64 s[0:1], -1
	s_cbranch_scc1 .LBB0_399

.LBB0_439:
	s_mov_b32 s36, s66
	s_mov_b32 s6, s39
	s_mov_b32 s37, s59
	v_lshl_add_u32 v221, s38, 1, v232
	ds_read_b64_tr_b16 v[196:197], v221 offset:24576
	ds_read_b64_tr_b16 v[198:199], v221 offset:25088
	v_add_f32_e32 v96, v80, v81
	v_add_f32_e32 v96, v82, v96
	v_add_f32_e32 v96, v83, v96
	v_add_f32_e32 v96, v84, v96
	v_add_f32_e32 v96, v85, v96
	v_cvt_pk_bf16_f32 v144, v80, v81
	v_cvt_pk_bf16_f32 v145, v82, v83
	s_waitcnt lgkmcnt(9)
	v_mfma_f32_32x32x16_bf16 v[112:127], v[188:191], v[128:131], 0
	ds_read_b64_tr_b16 v[80:81], v221 offset:28672
	ds_read_b64_tr_b16 v[82:83], v221 offset:29184
	v_add_f32_e32 v96, v86, v96
	v_add_f32_e32 v96, v87, v96
	v_add_f32_e32 v96, v88, v96
	v_add_f32_e32 v148, v89, v96
	v_cvt_pk_bf16_f32 v146, v84, v85
	v_cvt_pk_bf16_f32 v147, v86, v87
	s_waitcnt lgkmcnt(10)
	v_mfma_f32_32x32x16_bf16 v[96:111], v[180:183], v[128:131], 0
	ds_read_b64_tr_b16 v[84:85], v221 offset:25600
	ds_read_b64_tr_b16 v[86:87], v221 offset:26112
	v_add_f32_e32 v148, v90, v148
	v_add_f32_e32 v148, v91, v148
	v_add_f32_e32 v148, v92, v148
	v_add_f32_e32 v152, v93, v148
	v_cvt_pk_bf16_f32 v148, v88, v89
	v_cvt_pk_bf16_f32 v149, v90, v91
	s_waitcnt lgkmcnt(11)
	v_mfma_f32_32x32x16_bf16 v[112:127], v[184:187], v[132:135], v[112:127]
	ds_read_b64_tr_b16 v[88:89], v221 offset:29696
	ds_read_b64_tr_b16 v[90:91], v221 offset:30208
	v_add_f32_e32 v150, v94, v152
	v_add_f32_e32 v150, v95, v150
	v_add_f32_e32 v150, v64, v150
	v_add_f32_e32 v152, v65, v150
	v_cvt_pk_bf16_f32 v150, v92, v93
	v_cvt_pk_bf16_f32 v151, v94, v95
	s_waitcnt lgkmcnt(12)
	v_mfma_f32_32x32x16_bf16 v[96:111], v[176:179], v[132:135], v[96:111]
	ds_read_b64_tr_b16 v[92:93], v221 offset:26624
	ds_read_b64_tr_b16 v[94:95], v221 offset:27136
	v_add_f32_e32 v152, v66, v152
	v_add_f32_e32 v152, v67, v152
	v_add_f32_e32 v152, v68, v152
	v_add_f32_e32 v156, v69, v152
	v_cvt_pk_bf16_f32 v152, v64, v65
	v_cvt_pk_bf16_f32 v153, v66, v67
	s_waitcnt lgkmcnt(13)
	v_mfma_f32_32x32x16_bf16 v[112:127], v[172:175], v[136:139], v[112:127]
	ds_read_b64_tr_b16 v[200:201], v221 offset:30720
	ds_read_b64_tr_b16 v[202:203], v221 offset:31232
	v_add_f32_e32 v64, v70, v156
	v_add_f32_e32 v64, v71, v64
	v_add_f32_e32 v64, v72, v64
	v_add_f32_e32 v64, v73, v64
	v_cvt_pk_bf16_f32 v154, v68, v69
	v_cvt_pk_bf16_f32 v155, v70, v71
	s_waitcnt lgkmcnt(14)
	v_mfma_f32_32x32x16_bf16 v[96:111], v[168:171], v[136:139], v[96:111]
	ds_read_b64_tr_b16 v[208:209], v221 offset:27648
	ds_read_b64_tr_b16 v[210:211], v221 offset:28160
	v_add_f32_e32 v64, v74, v64
	v_add_f32_e32 v64, v75, v64
	v_add_f32_e32 v64, v76, v64
	v_add_f32_e32 v64, v77, v64
	v_cvt_pk_bf16_f32 v156, v72, v73
	v_cvt_pk_bf16_f32 v157, v74, v75
	s_waitcnt lgkmcnt(14)
	v_mfma_f32_32x32x16_bf16 v[112:127], v[164:167], v[140:143], v[112:127]
	ds_read_b64_tr_b16 v[72:73], v221 offset:31744
	ds_read_b64_tr_b16 v[74:75], v221 offset:32256
	v_add_f32_e32 v64, v78, v64
	v_add_f32_e32 v64, v79, v64
	v_cvt_pk_bf16_f32 v158, v76, v77
	v_cvt_pk_bf16_f32 v159, v78, v79
	v_mfma_f32_32x32x16_bf16 v[96:111], v[160:163], v[140:143], v[96:111]
	s_add_i32 s38, s59, s3
	v_add_f32_e32 v188, v233, v64
	s_mov_b32 m0, s38
	s_add_u32 s100, s98, s72
	s_addc_u32 s101, s99, s73
	global_load_lds_dwordx4 v238, s[100:101]
	s_lshl_b32 s38, s66, 1
	s_add_i32 s38, s38, s35
	s_mov_b32 m0, s38
	s_add_u32 s100, s98, s74
	s_addc_u32 s101, s99, s75
	global_load_lds_dwordx4 v239, s[100:101]
	s_addk_i32 s38, 0x2000
	s_mov_b32 m0, s38
	s_add_u32 s100, s98, s76
	s_addc_u32 s101, s99, s77
	global_load_lds_dwordx4 v239, s[100:101]
	s_waitcnt lgkmcnt(14)
	v_mfma_f32_32x32x16_bf16 v[48:63], v[144:147], v[196:199], v[48:63]
	v_exp_f32_e32 v112, v112
	v_exp_f32_e32 v113, v113
	ds_read_b64_tr_b16 v[76:77], v221 offset:32768
	ds_read_b64_tr_b16 v[78:79], v221 offset:33280
	s_waitcnt lgkmcnt(14)
	v_mfma_f32_32x32x16_bf16 v[32:47], v[144:147], v[80:83], v[32:47]
	v_exp_f32_e32 v114, v114
	v_exp_f32_e32 v115, v115
	ds_read_b64_tr_b16 v[80:81], v221 offset:36864
	ds_read_b64_tr_b16 v[82:83], v221 offset:37376
	v_add_u32_e32 v160, s36, v231
	ds_read_b128 v[68:71], v160
	ds_read_b128 v[64:67], v160 offset:512
	s_waitcnt lgkmcnt(14)
	v_mfma_f32_32x32x16_bf16 v[48:63], v[148:151], v[84:87], v[48:63]
	v_exp_f32_e32 v116, v116
	v_exp_f32_e32 v117, v117
	ds_read_b64_tr_b16 v[84:85], v221 offset:33792
	ds_read_b64_tr_b16 v[86:87], v221 offset:34304
	ds_read_b128 v[180:183], v160 offset:2048
	ds_read_b128 v[176:179], v160 offset:2560
	v_mfma_f32_32x32x16_bf16 v[32:47], v[148:151], v[88:91], v[32:47]
	v_exp_f32_e32 v118, v118
	v_exp_f32_e32 v119, v119
	ds_read_b64_tr_b16 v[88:89], v221 offset:37888
	ds_read_b64_tr_b16 v[90:91], v221 offset:38400
	ds_read_b128 v[172:175], v160 offset:4096
	ds_read_b128 v[168:171], v160 offset:4608
	s_waitcnt lgkmcnt(14)
	v_mfma_f32_32x32x16_bf16 v[48:63], v[152:155], v[92:95], v[48:63]
	v_exp_f32_e32 v120, v120
	v_exp_f32_e32 v121, v121
	ds_read_b64_tr_b16 v[92:93], v221 offset:34816
	ds_read_b64_tr_b16 v[94:95], v221 offset:35328
	ds_read_b128 v[164:167], v160 offset:6144
	ds_read_b128 v[160:163], v160 offset:6656
	v_mfma_f32_32x32x16_bf16 v[32:47], v[152:155], v[200:203], v[32:47]
	v_exp_f32_e32 v122, v122
	v_exp_f32_e32 v123, v123
	ds_read_b64_tr_b16 v[196:197], v221 offset:38912
	ds_read_b64_tr_b16 v[198:199], v221 offset:39424
	v_mfma_f32_32x32x16_bf16 v[48:63], v[156:159], v[208:211], v[48:63]
	v_exp_f32_e32 v124, v124
	v_exp_f32_e32 v125, v125
	ds_read_b64_tr_b16 v[200:201], v221 offset:35840
	ds_read_b64_tr_b16 v[202:203], v221 offset:36352
	v_mfma_f32_32x32x16_bf16 v[32:47], v[156:159], v[72:75], v[32:47]
	v_exp_f32_e32 v126, v126
	v_exp_f32_e32 v127, v127
	ds_read_b64_tr_b16 v[72:73], v221 offset:39936
	ds_read_b64_tr_b16 v[74:75], v221 offset:40448
	s_waitcnt lgkmcnt(14)
	v_mfma_f32_32x32x16_bf16 v[16:31], v[144:147], v[76:79], v[16:31]
	v_exp_f32_e32 v96, v96
	v_exp_f32_e32 v97, v97
	v_mfma_f32_32x32x16_bf16 v[0:15], v[144:147], v[80:83], v[0:15]
	v_exp_f32_e32 v98, v98
	v_exp_f32_e32 v99, v99
	v_mfma_f32_32x32x16_bf16 v[16:31], v[148:151], v[84:87], v[16:31]
	v_exp_f32_e32 v100, v100
	v_exp_f32_e32 v101, v101
	s_waitcnt lgkmcnt(12)
	v_mfma_f32_32x32x16_bf16 v[0:15], v[148:151], v[88:91], v[0:15]
	v_exp_f32_e32 v102, v102
	v_exp_f32_e32 v103, v103
	s_waitcnt lgkmcnt(8)
	v_mfma_f32_32x32x16_bf16 v[16:31], v[152:155], v[92:95], v[16:31]
	v_exp_f32_e32 v104, v104
	v_exp_f32_e32 v105, v105
	s_waitcnt lgkmcnt(4)
	v_mfma_f32_32x32x16_bf16 v[0:15], v[152:155], v[196:199], v[0:15]
	v_exp_f32_e32 v106, v106
	v_exp_f32_e32 v107, v107
	s_waitcnt lgkmcnt(2)
	v_mfma_f32_32x32x16_bf16 v[16:31], v[156:159], v[200:203], v[16:31]
	v_exp_f32_e32 v108, v108
	v_exp_f32_e32 v109, v109
	s_waitcnt lgkmcnt(0)
	v_mfma_f32_32x32x16_bf16 v[0:15], v[156:159], v[72:75], v[0:15]
	v_exp_f32_e32 v110, v110
	v_exp_f32_e32 v111, v111
	s_waitcnt vmcnt(3) lgkmcnt(0)
	s_barrier
	s_add_i32 s38, s66, 0x2000
	s_cmpk_lg_i32 s66, 0x4000
	s_cselect_b32 s59, s38, 0
	v_lshl_add_u32 v200, s37, 1, v232
	ds_read_b64_tr_b16 v[196:197], v200 offset:24576
	ds_read_b64_tr_b16 v[198:199], v200 offset:25088
	v_mfma_f32_32x32x16_bf16 v[80:95], v[68:71], v[128:131], 0
	v_add_f32_e32 v72, v112, v113
	v_add_f32_e32 v72, v114, v72
	v_add_f32_e32 v72, v115, v72
	v_add_f32_e32 v72, v116, v72
	v_add_f32_e32 v72, v117, v72
	v_cvt_pk_bf16_f32 v144, v112, v113
	v_cvt_pk_bf16_f32 v145, v114, v115
	ds_read_b64_tr_b16 v[112:113], v200 offset:28672
	ds_read_b64_tr_b16 v[114:115], v200 offset:29184
	v_add_f32_e32 v68, v118, v72
	v_add_f32_e32 v68, v119, v68
	v_add_f32_e32 v68, v120, v68
	v_add_f32_e32 v148, v121, v68
	v_mfma_f32_32x32x16_bf16 v[64:79], v[64:67], v[128:131], 0
	v_cvt_pk_bf16_f32 v146, v116, v117
	v_cvt_pk_bf16_f32 v147, v118, v119
	ds_read_b64_tr_b16 v[116:117], v200 offset:25600
	ds_read_b64_tr_b16 v[118:119], v200 offset:26112
	v_mfma_f32_32x32x16_bf16 v[80:95], v[180:183], v[132:135], v[80:95]
	v_add_f32_e32 v148, v122, v148
	v_add_f32_e32 v148, v123, v148
	v_add_f32_e32 v148, v124, v148
	v_add_f32_e32 v152, v125, v148
	v_cvt_pk_bf16_f32 v148, v120, v121
	v_cvt_pk_bf16_f32 v149, v122, v123
	ds_read_b64_tr_b16 v[120:121], v200 offset:29696
	ds_read_b64_tr_b16 v[122:123], v200 offset:30208
	v_mfma_f32_32x32x16_bf16 v[64:79], v[176:179], v[132:135], v[64:79]
	v_add_f32_e32 v150, v126, v152
	v_add_f32_e32 v150, v127, v150
	v_add_f32_e32 v150, v96, v150
	v_add_f32_e32 v152, v97, v150
	v_cvt_pk_bf16_f32 v150, v124, v125
	v_cvt_pk_bf16_f32 v151, v126, v127
	ds_read_b64_tr_b16 v[124:125], v200 offset:26624
	ds_read_b64_tr_b16 v[126:127], v200 offset:27136
	v_mfma_f32_32x32x16_bf16 v[80:95], v[172:175], v[136:139], v[80:95]
	v_add_f32_e32 v152, v98, v152
	v_add_f32_e32 v152, v99, v152
	v_add_f32_e32 v152, v100, v152
	v_add_f32_e32 v156, v101, v152
	v_cvt_pk_bf16_f32 v152, v96, v97
	v_cvt_pk_bf16_f32 v153, v98, v99
	ds_read_b64_tr_b16 v[96:97], v200 offset:30720
	ds_read_b64_tr_b16 v[98:99], v200 offset:31232
	v_mfma_f32_32x32x16_bf16 v[64:79], v[168:171], v[136:139], v[64:79]
	v_add_f32_e32 v154, v102, v156
	v_add_f32_e32 v154, v103, v154
	v_add_f32_e32 v154, v104, v154
	v_add_f32_e32 v156, v105, v154
	v_cvt_pk_bf16_f32 v154, v100, v101
	v_cvt_pk_bf16_f32 v155, v102, v103
	ds_read_b64_tr_b16 v[100:101], v200 offset:27648
	ds_read_b64_tr_b16 v[102:103], v200 offset:28160
	v_mfma_f32_32x32x16_bf16 v[80:95], v[164:167], v[140:143], v[80:95]
	v_add_f32_e32 v156, v106, v156
	v_add_f32_e32 v156, v107, v156
	v_add_f32_e32 v156, v108, v156
	v_add_f32_e32 v164, v109, v156
	v_cvt_pk_bf16_f32 v156, v104, v105
	v_cvt_pk_bf16_f32 v157, v106, v107
	ds_read_b64_tr_b16 v[104:105], v200 offset:31744
	ds_read_b64_tr_b16 v[106:107], v200 offset:32256
	v_mfma_f32_32x32x16_bf16 v[64:79], v[160:163], v[140:143], v[64:79]
	v_add_f32_e32 v158, v110, v164
	v_add_f32_e32 v160, v111, v158
	v_cvt_pk_bf16_f32 v158, v108, v109
	v_cvt_pk_bf16_f32 v159, v110, v111
	s_add_i32 s37, s66, s3
	s_mov_b32 m0, s37
	s_add_u32 s100, s98, s78
	s_addc_u32 s101, s99, s79
	global_load_lds_dwordx4 v238, s[100:101]
	s_lshl_b32 s37, s59, 1
	s_add_i32 s37, s37, s35
	s_mov_b32 m0, s37
	s_add_u32 s100, s98, s80
	s_addc_u32 s101, s99, s81
	global_load_lds_dwordx4 v239, s[100:101]
	s_addk_i32 s37, 0x2000
	s_mov_b32 m0, s37
	s_add_u32 s100, s98, s82
	s_addc_u32 s101, s99, s83
	global_load_lds_dwordx4 v239, s[100:101]
	v_add_f32_e32 v233, v188, v160
	s_waitcnt lgkmcnt(14)
	v_mfma_f32_32x32x16_bf16 v[48:63], v[144:147], v[196:199], v[48:63]
	v_exp_f32_e32 v80, v80
	v_exp_f32_e32 v81, v81
	ds_read_b64_tr_b16 v[108:109], v200 offset:32768
	ds_read_b64_tr_b16 v[110:111], v200 offset:33280
	s_waitcnt lgkmcnt(14)
	v_mfma_f32_32x32x16_bf16 v[32:47], v[144:147], v[112:115], v[32:47]
	v_exp_f32_e32 v82, v82
	v_exp_f32_e32 v83, v83
	ds_read_b64_tr_b16 v[112:113], v200 offset:36864
	ds_read_b64_tr_b16 v[114:115], v200 offset:37376
	v_add_u32_e32 v160, s59, v231
	ds_read_b128 v[188:191], v160
	ds_read_b128 v[180:183], v160 offset:512
	s_waitcnt lgkmcnt(14)
	v_mfma_f32_32x32x16_bf16 v[48:63], v[148:151], v[116:119], v[48:63]
	v_exp_f32_e32 v84, v84
	v_exp_f32_e32 v85, v85
	ds_read_b64_tr_b16 v[116:117], v200 offset:33792
	ds_read_b64_tr_b16 v[118:119], v200 offset:34304
	ds_read_b128 v[184:187], v160 offset:2048
	ds_read_b128 v[176:179], v160 offset:2560
	v_mfma_f32_32x32x16_bf16 v[32:47], v[148:151], v[120:123], v[32:47]
	v_exp_f32_e32 v86, v86
	v_exp_f32_e32 v87, v87
	ds_read_b64_tr_b16 v[120:121], v200 offset:37888
	ds_read_b64_tr_b16 v[122:123], v200 offset:38400
	ds_read_b128 v[172:175], v160 offset:4096
	ds_read_b128 v[168:171], v160 offset:4608
	s_waitcnt lgkmcnt(14)
	v_mfma_f32_32x32x16_bf16 v[48:63], v[152:155], v[124:127], v[48:63]
	v_exp_f32_e32 v88, v88
	v_exp_f32_e32 v89, v89
	ds_read_b64_tr_b16 v[124:125], v200 offset:34816
	ds_read_b64_tr_b16 v[126:127], v200 offset:35328
	ds_read_b128 v[164:167], v160 offset:6144
	ds_read_b128 v[160:163], v160 offset:6656
	v_mfma_f32_32x32x16_bf16 v[32:47], v[152:155], v[96:99], v[32:47]
	v_exp_f32_e32 v90, v90
	v_exp_f32_e32 v91, v91
	ds_read_b64_tr_b16 v[96:97], v200 offset:38912
	ds_read_b64_tr_b16 v[98:99], v200 offset:39424
	v_mfma_f32_32x32x16_bf16 v[48:63], v[156:159], v[100:103], v[48:63]
	v_exp_f32_e32 v92, v92
	v_exp_f32_e32 v93, v93
	ds_read_b64_tr_b16 v[100:101], v200 offset:35840
	ds_read_b64_tr_b16 v[102:103], v200 offset:36352
	v_mfma_f32_32x32x16_bf16 v[32:47], v[156:159], v[104:107], v[32:47]
	v_exp_f32_e32 v94, v94
	v_exp_f32_e32 v95, v95
	ds_read_b64_tr_b16 v[104:105], v200 offset:39936
	ds_read_b64_tr_b16 v[106:107], v200 offset:40448
	s_waitcnt lgkmcnt(14)
	v_mfma_f32_32x32x16_bf16 v[16:31], v[144:147], v[108:111], v[16:31]
	v_exp_f32_e32 v64, v64
	v_exp_f32_e32 v65, v65
	v_mfma_f32_32x32x16_bf16 v[0:15], v[144:147], v[112:115], v[0:15]
	v_exp_f32_e32 v66, v66
	v_exp_f32_e32 v67, v67
	v_mfma_f32_32x32x16_bf16 v[16:31], v[148:151], v[116:119], v[16:31]
	v_exp_f32_e32 v68, v68
	v_exp_f32_e32 v69, v69
	s_waitcnt lgkmcnt(12)
	v_mfma_f32_32x32x16_bf16 v[0:15], v[148:151], v[120:123], v[0:15]
	v_exp_f32_e32 v70, v70
	v_exp_f32_e32 v71, v71
	s_waitcnt lgkmcnt(8)
	v_mfma_f32_32x32x16_bf16 v[16:31], v[152:155], v[124:127], v[16:31]
	v_exp_f32_e32 v72, v72
	v_exp_f32_e32 v73, v73
	s_waitcnt lgkmcnt(4)
	v_mfma_f32_32x32x16_bf16 v[0:15], v[152:155], v[96:99], v[0:15]
	v_exp_f32_e32 v74, v74
	v_exp_f32_e32 v75, v75
	s_waitcnt lgkmcnt(2)
	v_mfma_f32_32x32x16_bf16 v[16:31], v[156:159], v[100:103], v[16:31]
	v_exp_f32_e32 v76, v76
	v_exp_f32_e32 v77, v77
	s_waitcnt lgkmcnt(0)
	v_mfma_f32_32x32x16_bf16 v[0:15], v[156:159], v[104:107], v[0:15]
	v_exp_f32_e32 v78, v78
	v_exp_f32_e32 v79, v79
	s_add_i32 s37, s59, 0x2000
	s_cmpk_lg_i32 s59, 0x4000
	s_cselect_b32 s66, s37, 0
	s_add_i32 s39, s6, 2
	s_waitcnt vmcnt(3) lgkmcnt(0)
	s_barrier
	s_add_u32 s4, s4, 0x20000
	s_addc_u32 s5, s5, 0
	s_add_u32 s98, s98, 0x20000
	s_addc_u32 s99, s99, 0
	s_cmp_gt_u32 s39, s57
	s_mov_b32 s38, s36
	s_cbranch_scc0 .LBB0_439
	s_add_i32 s6, s6, -3
	s_branch .LBB0_443
